# ACT stores without the write-through modifier (chunk-major ACT: whole 1 KB chunks per store instruction)
# speedup vs baseline: 1.0067x; 1.0067x over previous
.Lg2_a_kdone3:
	s_nop 7
	s_nop 1
	v_mov_b32_e32 v176, v138
	v_mul_f32_e32 v162, 0xbfb8aa3b, v2
	v_mul_f32_e32 v163, 0xbfb8aa3b, v3
	v_mul_f32_e32 v164, 0xbfb8aa3b, v4
	v_mul_f32_e32 v165, 0xbfb8aa3b, v5
	v_exp_f32_e32 v162, v162
	v_exp_f32_e32 v163, v163
	v_exp_f32_e32 v164, v164
	v_exp_f32_e32 v165, v165
	v_add_f32_e32 v162, 1.0, v162
	v_add_f32_e32 v163, 1.0, v163
	v_add_f32_e32 v164, 1.0, v164
	v_add_f32_e32 v165, 1.0, v165
	v_rcp_f32_e32 v162, v162
	v_rcp_f32_e32 v163, v163
	v_rcp_f32_e32 v164, v164
	v_rcp_f32_e32 v165, v165
	v_mul_f32_e32 v162, v2, v162
	v_mul_f32_e32 v163, v3, v163
	v_mul_f32_e32 v164, v4, v164
	v_mul_f32_e32 v165, v5, v165
	v_mul_f32_e32 v162, v10, v162
	v_mul_f32_e32 v163, v11, v163
	v_mul_f32_e32 v164, v12, v164
	v_mul_f32_e32 v165, v13, v165
	v_cvt_pk_bf16_f32 v168, v162, v163
	v_cvt_pk_bf16_f32 v169, v164, v165
	v_mul_f32_e32 v162, 0xbfb8aa3b, v6
	v_mul_f32_e32 v163, 0xbfb8aa3b, v7
	v_mul_f32_e32 v164, 0xbfb8aa3b, v8
	v_mul_f32_e32 v165, 0xbfb8aa3b, v9
	v_exp_f32_e32 v162, v162
	v_exp_f32_e32 v163, v163
	v_exp_f32_e32 v164, v164
	v_exp_f32_e32 v165, v165
	v_add_f32_e32 v162, 1.0, v162
	v_add_f32_e32 v163, 1.0, v163
	v_add_f32_e32 v164, 1.0, v164
	v_add_f32_e32 v165, 1.0, v165
	v_rcp_f32_e32 v162, v162
	v_rcp_f32_e32 v163, v163
	v_rcp_f32_e32 v164, v164
	v_rcp_f32_e32 v165, v165
	v_mul_f32_e32 v162, v6, v162
	v_mul_f32_e32 v163, v7, v163
	v_mul_f32_e32 v164, v8, v164
	v_mul_f32_e32 v165, v9, v165
	v_mul_f32_e32 v162, v14, v162
	v_mul_f32_e32 v163, v15, v163
	v_mul_f32_e32 v164, v16, v164
	v_mul_f32_e32 v165, v17, v165
	v_cvt_pk_bf16_f32 v170, v162, v163
	v_cvt_pk_bf16_f32 v171, v164, v165
	s_nop 1
	v_permlane16_swap_b32_e32 v168, v170
	v_permlane16_swap_b32_e32 v169, v171
	global_store_dwordx4 v176, v[168:171], s[4:5] offset:0
	v_mul_f32_e32 v162, 0xbfb8aa3b, v66
	v_mul_f32_e32 v163, 0xbfb8aa3b, v67
	v_mul_f32_e32 v164, 0xbfb8aa3b, v68
	v_mul_f32_e32 v165, 0xbfb8aa3b, v69
	v_exp_f32_e32 v162, v162
	v_exp_f32_e32 v163, v163
	v_exp_f32_e32 v164, v164
	v_exp_f32_e32 v165, v165
	v_add_f32_e32 v162, 1.0, v162
	v_add_f32_e32 v163, 1.0, v163
	v_add_f32_e32 v164, 1.0, v164
	v_add_f32_e32 v165, 1.0, v165
	v_rcp_f32_e32 v162, v162
	v_rcp_f32_e32 v163, v163
	v_rcp_f32_e32 v164, v164
	v_rcp_f32_e32 v165, v165
	v_mul_f32_e32 v162, v66, v162
	v_mul_f32_e32 v163, v67, v163
	v_mul_f32_e32 v164, v68, v164
	v_mul_f32_e32 v165, v69, v165
	v_mul_f32_e32 v162, v74, v162
	v_mul_f32_e32 v163, v75, v163
	v_mul_f32_e32 v164, v76, v164
	v_mul_f32_e32 v165, v77, v165
	v_cvt_pk_bf16_f32 v172, v162, v163
	v_cvt_pk_bf16_f32 v173, v164, v165
	v_mul_f32_e32 v162, 0xbfb8aa3b, v70
	v_mul_f32_e32 v163, 0xbfb8aa3b, v71
	v_mul_f32_e32 v164, 0xbfb8aa3b, v72
	v_mul_f32_e32 v165, 0xbfb8aa3b, v73
	v_exp_f32_e32 v162, v162
	v_exp_f32_e32 v163, v163
	v_exp_f32_e32 v164, v164
	v_exp_f32_e32 v165, v165
	v_add_f32_e32 v162, 1.0, v162
	v_add_f32_e32 v163, 1.0, v163
	v_add_f32_e32 v164, 1.0, v164
	v_add_f32_e32 v165, 1.0, v165
	v_rcp_f32_e32 v162, v162
	v_rcp_f32_e32 v163, v163
	v_rcp_f32_e32 v164, v164
	v_rcp_f32_e32 v165, v165
	v_mul_f32_e32 v162, v70, v162
	v_mul_f32_e32 v163, v71, v163
	v_mul_f32_e32 v164, v72, v164
	v_mul_f32_e32 v165, v73, v165
	v_mul_f32_e32 v162, v78, v162
	v_mul_f32_e32 v163, v79, v163
	v_mul_f32_e32 v164, v80, v164
	v_mul_f32_e32 v165, v81, v165
	v_cvt_pk_bf16_f32 v174, v162, v163
	v_cvt_pk_bf16_f32 v175, v164, v165
	s_nop 1
	v_permlane16_swap_b32_e32 v172, v174
	v_permlane16_swap_b32_e32 v173, v175
	global_store_dwordx4 v176, v[172:175], s[4:5] offset:2048
	v_add_u32_e32 v176, 0x16000, v176
	v_mul_f32_e32 v162, 0xbfb8aa3b, v18
	v_mul_f32_e32 v163, 0xbfb8aa3b, v19
	v_mul_f32_e32 v164, 0xbfb8aa3b, v20
	v_mul_f32_e32 v165, 0xbfb8aa3b, v21
	v_exp_f32_e32 v162, v162
	v_exp_f32_e32 v163, v163
	v_exp_f32_e32 v164, v164
	v_exp_f32_e32 v165, v165
	v_add_f32_e32 v162, 1.0, v162
	v_add_f32_e32 v163, 1.0, v163
	v_add_f32_e32 v164, 1.0, v164
	v_add_f32_e32 v165, 1.0, v165
	v_rcp_f32_e32 v162, v162
	v_rcp_f32_e32 v163, v163
	v_rcp_f32_e32 v164, v164
	v_rcp_f32_e32 v165, v165
	v_mul_f32_e32 v162, v18, v162
	v_mul_f32_e32 v163, v19, v163
	v_mul_f32_e32 v164, v20, v164
	v_mul_f32_e32 v165, v21, v165
	v_mul_f32_e32 v162, v26, v162
	v_mul_f32_e32 v163, v27, v163
	v_mul_f32_e32 v164, v28, v164
	v_mul_f32_e32 v165, v29, v165
	v_cvt_pk_bf16_f32 v168, v162, v163
	v_cvt_pk_bf16_f32 v169, v164, v165
	v_mul_f32_e32 v162, 0xbfb8aa3b, v22
	v_mul_f32_e32 v163, 0xbfb8aa3b, v23
	v_mul_f32_e32 v164, 0xbfb8aa3b, v24
	v_mul_f32_e32 v165, 0xbfb8aa3b, v25
	v_exp_f32_e32 v162, v162
	v_exp_f32_e32 v163, v163
	v_exp_f32_e32 v164, v164
	v_exp_f32_e32 v165, v165
	v_add_f32_e32 v162, 1.0, v162
	v_add_f32_e32 v163, 1.0, v163
	v_add_f32_e32 v164, 1.0, v164
	v_add_f32_e32 v165, 1.0, v165
	v_rcp_f32_e32 v162, v162
	v_rcp_f32_e32 v163, v163
	v_rcp_f32_e32 v164, v164
	v_rcp_f32_e32 v165, v165
	v_mul_f32_e32 v162, v22, v162
	v_mul_f32_e32 v163, v23, v163
	v_mul_f32_e32 v164, v24, v164
	v_mul_f32_e32 v165, v25, v165
	v_mul_f32_e32 v162, v30, v162
	v_mul_f32_e32 v163, v31, v163
	v_mul_f32_e32 v164, v32, v164
	v_mul_f32_e32 v165, v33, v165
	v_cvt_pk_bf16_f32 v170, v162, v163
	v_cvt_pk_bf16_f32 v171, v164, v165
	s_nop 1
	v_permlane16_swap_b32_e32 v168, v170
	v_permlane16_swap_b32_e32 v169, v171
	global_store_dwordx4 v176, v[168:171], s[4:5] offset:0
	v_mul_f32_e32 v162, 0xbfb8aa3b, v82
	v_mul_f32_e32 v163, 0xbfb8aa3b, v83
	v_mul_f32_e32 v164, 0xbfb8aa3b, v84
	v_mul_f32_e32 v165, 0xbfb8aa3b, v85
	v_exp_f32_e32 v162, v162
	v_exp_f32_e32 v163, v163
	v_exp_f32_e32 v164, v164
	v_exp_f32_e32 v165, v165
	v_add_f32_e32 v162, 1.0, v162
	v_add_f32_e32 v163, 1.0, v163
	v_add_f32_e32 v164, 1.0, v164
	v_add_f32_e32 v165, 1.0, v165
	v_rcp_f32_e32 v162, v162
	v_rcp_f32_e32 v163, v163
	v_rcp_f32_e32 v164, v164
	v_rcp_f32_e32 v165, v165
	v_mul_f32_e32 v162, v82, v162
	v_mul_f32_e32 v163, v83, v163
	v_mul_f32_e32 v164, v84, v164
	v_mul_f32_e32 v165, v85, v165
	v_mul_f32_e32 v162, v90, v162
	v_mul_f32_e32 v163, v91, v163
	v_mul_f32_e32 v164, v92, v164
	v_mul_f32_e32 v165, v93, v165
	v_cvt_pk_bf16_f32 v172, v162, v163
	v_cvt_pk_bf16_f32 v173, v164, v165
	v_mul_f32_e32 v162, 0xbfb8aa3b, v86
	v_mul_f32_e32 v163, 0xbfb8aa3b, v87
	v_mul_f32_e32 v164, 0xbfb8aa3b, v88
	v_mul_f32_e32 v165, 0xbfb8aa3b, v89
	v_exp_f32_e32 v162, v162
	v_exp_f32_e32 v163, v163
	v_exp_f32_e32 v164, v164
	v_exp_f32_e32 v165, v165
	v_add_f32_e32 v162, 1.0, v162
	v_add_f32_e32 v163, 1.0, v163
	v_add_f32_e32 v164, 1.0, v164
	v_add_f32_e32 v165, 1.0, v165
	v_rcp_f32_e32 v162, v162
	v_rcp_f32_e32 v163, v163
	v_rcp_f32_e32 v164, v164
	v_rcp_f32_e32 v165, v165
	v_mul_f32_e32 v162, v86, v162
	v_mul_f32_e32 v163, v87, v163
	v_mul_f32_e32 v164, v88, v164
	v_mul_f32_e32 v165, v89, v165
	v_mul_f32_e32 v162, v94, v162
	v_mul_f32_e32 v163, v95, v163
	v_mul_f32_e32 v164, v96, v164
	v_mul_f32_e32 v165, v97, v165
	v_cvt_pk_bf16_f32 v174, v162, v163
	v_cvt_pk_bf16_f32 v175, v164, v165
	s_nop 1
	v_permlane16_swap_b32_e32 v172, v174
	v_permlane16_swap_b32_e32 v173, v175
	global_store_dwordx4 v176, v[172:175], s[4:5] offset:2048
	v_add_u32_e32 v176, 0x16000, v176
	v_mul_f32_e32 v162, 0xbfb8aa3b, v34
	v_mul_f32_e32 v163, 0xbfb8aa3b, v35
	v_mul_f32_e32 v164, 0xbfb8aa3b, v36
	v_mul_f32_e32 v165, 0xbfb8aa3b, v37
	v_exp_f32_e32 v162, v162
	v_exp_f32_e32 v163, v163
	v_exp_f32_e32 v164, v164
	v_exp_f32_e32 v165, v165
	v_add_f32_e32 v162, 1.0, v162
	v_add_f32_e32 v163, 1.0, v163
	v_add_f32_e32 v164, 1.0, v164
	v_add_f32_e32 v165, 1.0, v165
	v_rcp_f32_e32 v162, v162
	v_rcp_f32_e32 v163, v163
	v_rcp_f32_e32 v164, v164
	v_rcp_f32_e32 v165, v165
	v_mul_f32_e32 v162, v34, v162
	v_mul_f32_e32 v163, v35, v163
	v_mul_f32_e32 v164, v36, v164
	v_mul_f32_e32 v165, v37, v165
	v_mul_f32_e32 v162, v42, v162
	v_mul_f32_e32 v163, v43, v163
	v_mul_f32_e32 v164, v44, v164
	v_mul_f32_e32 v165, v45, v165
	v_cvt_pk_bf16_f32 v168, v162, v163
	v_cvt_pk_bf16_f32 v169, v164, v165
	v_mul_f32_e32 v162, 0xbfb8aa3b, v38
	v_mul_f32_e32 v163, 0xbfb8aa3b, v39
	v_mul_f32_e32 v164, 0xbfb8aa3b, v40
	v_mul_f32_e32 v165, 0xbfb8aa3b, v41
	v_exp_f32_e32 v162, v162
	v_exp_f32_e32 v163, v163
	v_exp_f32_e32 v164, v164
	v_exp_f32_e32 v165, v165
	v_add_f32_e32 v162, 1.0, v162
	v_add_f32_e32 v163, 1.0, v163
	v_add_f32_e32 v164, 1.0, v164
	v_add_f32_e32 v165, 1.0, v165
	v_rcp_f32_e32 v162, v162
	v_rcp_f32_e32 v163, v163
	v_rcp_f32_e32 v164, v164
	v_rcp_f32_e32 v165, v165
	v_mul_f32_e32 v162, v38, v162
	v_mul_f32_e32 v163, v39, v163
	v_mul_f32_e32 v164, v40, v164
	v_mul_f32_e32 v165, v41, v165
	v_mul_f32_e32 v162, v46, v162
	v_mul_f32_e32 v163, v47, v163
	v_mul_f32_e32 v164, v48, v164
	v_mul_f32_e32 v165, v49, v165
	v_cvt_pk_bf16_f32 v170, v162, v163
	v_cvt_pk_bf16_f32 v171, v164, v165
	s_nop 1
	v_permlane16_swap_b32_e32 v168, v170
	v_permlane16_swap_b32_e32 v169, v171
	global_store_dwordx4 v176, v[168:171], s[4:5] offset:0
	v_mul_f32_e32 v162, 0xbfb8aa3b, v98
	v_mul_f32_e32 v163, 0xbfb8aa3b, v99
	v_mul_f32_e32 v164, 0xbfb8aa3b, v100
	v_mul_f32_e32 v165, 0xbfb8aa3b, v101
	v_exp_f32_e32 v162, v162
	v_exp_f32_e32 v163, v163
	v_exp_f32_e32 v164, v164
	v_exp_f32_e32 v165, v165
	v_add_f32_e32 v162, 1.0, v162
	v_add_f32_e32 v163, 1.0, v163
	v_add_f32_e32 v164, 1.0, v164
	v_add_f32_e32 v165, 1.0, v165
	v_rcp_f32_e32 v162, v162
	v_rcp_f32_e32 v163, v163
	v_rcp_f32_e32 v164, v164
	v_rcp_f32_e32 v165, v165
	v_mul_f32_e32 v162, v98, v162
	v_mul_f32_e32 v163, v99, v163
	v_mul_f32_e32 v164, v100, v164
	v_mul_f32_e32 v165, v101, v165
	v_mul_f32_e32 v162, v106, v162
	v_mul_f32_e32 v163, v107, v163
	v_mul_f32_e32 v164, v108, v164
	v_mul_f32_e32 v165, v109, v165
	v_cvt_pk_bf16_f32 v172, v162, v163
	v_cvt_pk_bf16_f32 v173, v164, v165
	v_mul_f32_e32 v162, 0xbfb8aa3b, v102
	v_mul_f32_e32 v163, 0xbfb8aa3b, v103
	v_mul_f32_e32 v164, 0xbfb8aa3b, v104
	v_mul_f32_e32 v165, 0xbfb8aa3b, v105
	v_exp_f32_e32 v162, v162
	v_exp_f32_e32 v163, v163
	v_exp_f32_e32 v164, v164
	v_exp_f32_e32 v165, v165
	v_add_f32_e32 v162, 1.0, v162
	v_add_f32_e32 v163, 1.0, v163
	v_add_f32_e32 v164, 1.0, v164
	v_add_f32_e32 v165, 1.0, v165
	v_rcp_f32_e32 v162, v162
	v_rcp_f32_e32 v163, v163
	v_rcp_f32_e32 v164, v164
	v_rcp_f32_e32 v165, v165
	v_mul_f32_e32 v162, v102, v162
	v_mul_f32_e32 v163, v103, v163
	v_mul_f32_e32 v164, v104, v164
	v_mul_f32_e32 v165, v105, v165
	v_mul_f32_e32 v162, v110, v162
	v_mul_f32_e32 v163, v111, v163
	v_mul_f32_e32 v164, v112, v164
	v_mul_f32_e32 v165, v113, v165
	v_cvt_pk_bf16_f32 v174, v162, v163
	v_cvt_pk_bf16_f32 v175, v164, v165
	s_nop 1
	v_permlane16_swap_b32_e32 v172, v174
	v_permlane16_swap_b32_e32 v173, v175
	global_store_dwordx4 v176, v[172:175], s[4:5] offset:2048
	v_add_u32_e32 v176, 0x16000, v176
	v_mul_f32_e32 v162, 0xbfb8aa3b, v50
	v_mul_f32_e32 v163, 0xbfb8aa3b, v51
	v_mul_f32_e32 v164, 0xbfb8aa3b, v52
	v_mul_f32_e32 v165, 0xbfb8aa3b, v53
	v_exp_f32_e32 v162, v162
	v_exp_f32_e32 v163, v163
	v_exp_f32_e32 v164, v164
	v_exp_f32_e32 v165, v165
	v_add_f32_e32 v162, 1.0, v162
	v_add_f32_e32 v163, 1.0, v163
	v_add_f32_e32 v164, 1.0, v164
	v_add_f32_e32 v165, 1.0, v165
	v_rcp_f32_e32 v162, v162
	v_rcp_f32_e32 v163, v163
	v_rcp_f32_e32 v164, v164
	v_rcp_f32_e32 v165, v165
	v_mul_f32_e32 v162, v50, v162
	v_mul_f32_e32 v163, v51, v163
	v_mul_f32_e32 v164, v52, v164
	v_mul_f32_e32 v165, v53, v165
	v_mul_f32_e32 v162, v58, v162
	v_mul_f32_e32 v163, v59, v163
	v_mul_f32_e32 v164, v60, v164
	v_mul_f32_e32 v165, v61, v165
	v_cvt_pk_bf16_f32 v168, v162, v163
	v_cvt_pk_bf16_f32 v169, v164, v165
	v_mul_f32_e32 v162, 0xbfb8aa3b, v54
	v_mul_f32_e32 v163, 0xbfb8aa3b, v55
	v_mul_f32_e32 v164, 0xbfb8aa3b, v56
	v_mul_f32_e32 v165, 0xbfb8aa3b, v57
	v_exp_f32_e32 v162, v162
	v_exp_f32_e32 v163, v163
	v_exp_f32_e32 v164, v164
	v_exp_f32_e32 v165, v165
	v_add_f32_e32 v162, 1.0, v162
	v_add_f32_e32 v163, 1.0, v163
	v_add_f32_e32 v164, 1.0, v164
	v_add_f32_e32 v165, 1.0, v165
	v_rcp_f32_e32 v162, v162
	v_rcp_f32_e32 v163, v163
	v_rcp_f32_e32 v164, v164
	v_rcp_f32_e32 v165, v165
	v_mul_f32_e32 v162, v54, v162
	v_mul_f32_e32 v163, v55, v163
	v_mul_f32_e32 v164, v56, v164
	v_mul_f32_e32 v165, v57, v165
	v_mul_f32_e32 v162, v62, v162
	v_mul_f32_e32 v163, v63, v163
	v_mul_f32_e32 v164, v64, v164
	v_mul_f32_e32 v165, v65, v165
	v_cvt_pk_bf16_f32 v170, v162, v163
	v_cvt_pk_bf16_f32 v171, v164, v165
	s_nop 1
	v_permlane16_swap_b32_e32 v168, v170
	v_permlane16_swap_b32_e32 v169, v171
	global_store_dwordx4 v176, v[168:171], s[4:5] offset:0
	v_mul_f32_e32 v162, 0xbfb8aa3b, v114
	v_mul_f32_e32 v163, 0xbfb8aa3b, v115
	v_mul_f32_e32 v164, 0xbfb8aa3b, v116
	v_mul_f32_e32 v165, 0xbfb8aa3b, v117
	v_exp_f32_e32 v162, v162
	v_exp_f32_e32 v163, v163
	v_exp_f32_e32 v164, v164
	v_exp_f32_e32 v165, v165
	v_add_f32_e32 v162, 1.0, v162
	v_add_f32_e32 v163, 1.0, v163
	v_add_f32_e32 v164, 1.0, v164
	v_add_f32_e32 v165, 1.0, v165
	v_rcp_f32_e32 v162, v162
	v_rcp_f32_e32 v163, v163
	v_rcp_f32_e32 v164, v164
	v_rcp_f32_e32 v165, v165
	v_mul_f32_e32 v162, v114, v162
	v_mul_f32_e32 v163, v115, v163
	v_mul_f32_e32 v164, v116, v164
	v_mul_f32_e32 v165, v117, v165
	v_mul_f32_e32 v162, v122, v162
	v_mul_f32_e32 v163, v123, v163
	v_mul_f32_e32 v164, v124, v164
	v_mul_f32_e32 v165, v125, v165
	v_cvt_pk_bf16_f32 v172, v162, v163
	v_cvt_pk_bf16_f32 v173, v164, v165
	v_mul_f32_e32 v162, 0xbfb8aa3b, v118
	v_mul_f32_e32 v163, 0xbfb8aa3b, v119
	v_mul_f32_e32 v164, 0xbfb8aa3b, v120
	v_mul_f32_e32 v165, 0xbfb8aa3b, v121
	v_exp_f32_e32 v162, v162
	v_exp_f32_e32 v163, v163
	v_exp_f32_e32 v164, v164
	v_exp_f32_e32 v165, v165
	v_add_f32_e32 v162, 1.0, v162
	v_add_f32_e32 v163, 1.0, v163
	v_add_f32_e32 v164, 1.0, v164
	v_add_f32_e32 v165, 1.0, v165
	v_rcp_f32_e32 v162, v162
	v_rcp_f32_e32 v163, v163
	v_rcp_f32_e32 v164, v164
	v_rcp_f32_e32 v165, v165
	v_mul_f32_e32 v162, v118, v162
	v_mul_f32_e32 v163, v119, v163
	v_mul_f32_e32 v164, v120, v164
	v_mul_f32_e32 v165, v121, v165
	v_mul_f32_e32 v162, v126, v162
	v_mul_f32_e32 v163, v127, v163
	v_mul_f32_e32 v164, v128, v164
	v_mul_f32_e32 v165, v129, v165
	v_cvt_pk_bf16_f32 v174, v162, v163
	v_cvt_pk_bf16_f32 v175, v164, v165
	s_nop 1
	v_permlane16_swap_b32_e32 v172, v174
	v_permlane16_swap_b32_e32 v173, v175
	global_store_dwordx4 v176, v[172:175], s[4:5] offset:2048
	s_add_u32 s10, s10, 32
	s_cmp_lt_u32 s10, 64
	s_cbranch_scc1 .Lg2_a_item1
	s_cmp_lt_u32 s15, 8
	s_cbranch_scc0 .Lg2_a_noleft5
	s_lshr_b32 s12, s15, 2
	s_add_u32 s12, s12, 4
	s_mov_b32 s11, 10
	s_and_b32 s16, s15, 3
	s_lshl_b32 s16, s16, 6
	s_and_b32 s17, s14, 3
	s_mul_i32 s17, s17, 6
	s_add_u32 s12, s12, s17
	s_lshl_b32 s12, s12, 8
	s_add_u32 s12, s12, s16
	s_lshr_b32 s17, s14, 2
	s_mul_i32 s17, s17, 22
	s_lshl_b32 s11, s11, 1
	s_add_u32 s11, s11, s17
	s_lshl_b32 s16, s12, 11
	s_add_u32 s0, s24, s16
	s_addc_u32 s1, s25, 0
	s_lshl_b32 s16, s11, 18
	s_add_u32 s2, s40, s16
	s_addc_u32 s3, s41, 0
	s_mul_i32 s16, s12, 0x1600
	s_lshl_b32 s17, s11, 11
	s_add_u32 s16, s16, s17
	s_add_u32 s4, s26, s16
	s_addc_u32 s5, s27, 0
	v_lshrrev_b32_e32 v141, 8, v142
	v_lshlrev_b32_e32 v141, 17, v141
	v_sub_u32_e32 v141, v136, v141
	s_and_b32 s17, s6, 0xfff
	s_add_u32 m0, s17, 0x0
	s_nop 0
	global_load_lds_dwordx4 v141, s[0:1]
	s_add_u32 m0, s6, 0x4000
	s_nop 0
	global_load_lds_dwordx4 v136, s[2:3]
	s_add_u32 m0, s6, 0x6000
	s_nop 0
	global_load_lds_dwordx4 v137, s[2:3]
	s_add_u32 s0, s0, 1024
	s_addc_u32 s1, s1, 0
	s_add_u32 s2, s2, 1024
	s_addc_u32 s3, s3, 0
	s_add_u32 m0, s17, 0x8000
	s_nop 0
	global_load_lds_dwordx4 v141, s[0:1]
	s_add_u32 m0, s6, 0xc000
	s_nop 0
	global_load_lds_dwordx4 v136, s[2:3]
	s_add_u32 m0, s6, 0xe000
	s_nop 0
	global_load_lds_dwordx4 v137, s[2:3]
	s_add_u32 s0, s0, 1024
	s_addc_u32 s1, s1, 0
	s_add_u32 s2, s2, 1024
	s_addc_u32 s3, s3, 0
	s_add_u32 m0, s17, 0x10000
	s_nop 0
	global_load_lds_dwordx4 v141, s[0:1]
	s_add_u32 m0, s6, 0x14000
	s_nop 0
	global_load_lds_dwordx4 v136, s[2:3]
	s_add_u32 m0, s6, 0x16000
	s_nop 0
	global_load_lds_dwordx4 v137, s[2:3]
	s_add_u32 s0, s0, 1024
	s_addc_u32 s1, s1, 0
	s_add_u32 s2, s2, 1024
	s_addc_u32 s3, s3, 0
	v_lshrrev_b32_e32 v140, 7, v142
	v_lshlrev_b32_e32 v139, 12, v140
	v_sub_u32_e32 v134, v134, v139
	v_lshl_add_u32 v134, v140, 10, v134
	v_mul_u32_u24_e32 v139, 0x42000, v140
	v_sub_u32_e32 v138, v138, v139
	v_mov_b32_e32 v2, 0
	v_mov_b32_e32 v3, 0
	v_mov_b32_e32 v4, 0
	v_mov_b32_e32 v5, 0
	v_mov_b32_e32 v6, 0
	v_mov_b32_e32 v7, 0
	v_mov_b32_e32 v8, 0
	v_mov_b32_e32 v9, 0
	v_mov_b32_e32 v10, 0
	v_mov_b32_e32 v11, 0
	v_mov_b32_e32 v12, 0
	v_mov_b32_e32 v13, 0
	v_mov_b32_e32 v14, 0
	v_mov_b32_e32 v15, 0
	v_mov_b32_e32 v16, 0
	v_mov_b32_e32 v17, 0
	v_mov_b32_e32 v66, 0
	v_mov_b32_e32 v67, 0
	v_mov_b32_e32 v68, 0
	v_mov_b32_e32 v69, 0
	v_mov_b32_e32 v70, 0
	v_mov_b32_e32 v71, 0
	v_mov_b32_e32 v72, 0
	v_mov_b32_e32 v73, 0
	v_mov_b32_e32 v74, 0
	v_mov_b32_e32 v75, 0
	v_mov_b32_e32 v76, 0
	v_mov_b32_e32 v77, 0
	v_mov_b32_e32 v78, 0
	v_mov_b32_e32 v79, 0
	v_mov_b32_e32 v80, 0
	v_mov_b32_e32 v81, 0

.Lg2_a_kdone7:
	s_nop 7
	s_nop 1
	v_mov_b32_e32 v176, v138
	v_mul_f32_e32 v162, 0xbfb8aa3b, v2
	v_mul_f32_e32 v163, 0xbfb8aa3b, v3
	v_mul_f32_e32 v164, 0xbfb8aa3b, v4
	v_mul_f32_e32 v165, 0xbfb8aa3b, v5
	v_exp_f32_e32 v162, v162
	v_exp_f32_e32 v163, v163
	v_exp_f32_e32 v164, v164
	v_exp_f32_e32 v165, v165
	v_add_f32_e32 v162, 1.0, v162
	v_add_f32_e32 v163, 1.0, v163
	v_add_f32_e32 v164, 1.0, v164
	v_add_f32_e32 v165, 1.0, v165
	v_rcp_f32_e32 v162, v162
	v_rcp_f32_e32 v163, v163
	v_rcp_f32_e32 v164, v164
	v_rcp_f32_e32 v165, v165
	v_mul_f32_e32 v162, v2, v162
	v_mul_f32_e32 v163, v3, v163
	v_mul_f32_e32 v164, v4, v164
	v_mul_f32_e32 v165, v5, v165
	v_mul_f32_e32 v162, v10, v162
	v_mul_f32_e32 v163, v11, v163
	v_mul_f32_e32 v164, v12, v164
	v_mul_f32_e32 v165, v13, v165
	v_cvt_pk_bf16_f32 v168, v162, v163
	v_cvt_pk_bf16_f32 v169, v164, v165
	v_mul_f32_e32 v162, 0xbfb8aa3b, v6
	v_mul_f32_e32 v163, 0xbfb8aa3b, v7
	v_mul_f32_e32 v164, 0xbfb8aa3b, v8
	v_mul_f32_e32 v165, 0xbfb8aa3b, v9
	v_exp_f32_e32 v162, v162
	v_exp_f32_e32 v163, v163
	v_exp_f32_e32 v164, v164
	v_exp_f32_e32 v165, v165
	v_add_f32_e32 v162, 1.0, v162
	v_add_f32_e32 v163, 1.0, v163
	v_add_f32_e32 v164, 1.0, v164
	v_add_f32_e32 v165, 1.0, v165
	v_rcp_f32_e32 v162, v162
	v_rcp_f32_e32 v163, v163
	v_rcp_f32_e32 v164, v164
	v_rcp_f32_e32 v165, v165
	v_mul_f32_e32 v162, v6, v162
	v_mul_f32_e32 v163, v7, v163
	v_mul_f32_e32 v164, v8, v164
	v_mul_f32_e32 v165, v9, v165
	v_mul_f32_e32 v162, v14, v162
	v_mul_f32_e32 v163, v15, v163
	v_mul_f32_e32 v164, v16, v164
	v_mul_f32_e32 v165, v17, v165
	v_cvt_pk_bf16_f32 v170, v162, v163
	v_cvt_pk_bf16_f32 v171, v164, v165
	s_nop 1
	v_permlane16_swap_b32_e32 v168, v170
	v_permlane16_swap_b32_e32 v169, v171
	global_store_dwordx4 v176, v[168:171], s[4:5] offset:0
	v_mul_f32_e32 v162, 0xbfb8aa3b, v66
	v_mul_f32_e32 v163, 0xbfb8aa3b, v67
	v_mul_f32_e32 v164, 0xbfb8aa3b, v68
	v_mul_f32_e32 v165, 0xbfb8aa3b, v69
	v_exp_f32_e32 v162, v162
	v_exp_f32_e32 v163, v163
	v_exp_f32_e32 v164, v164
	v_exp_f32_e32 v165, v165
	v_add_f32_e32 v162, 1.0, v162
	v_add_f32_e32 v163, 1.0, v163
	v_add_f32_e32 v164, 1.0, v164
	v_add_f32_e32 v165, 1.0, v165
	v_rcp_f32_e32 v162, v162
	v_rcp_f32_e32 v163, v163
	v_rcp_f32_e32 v164, v164
	v_rcp_f32_e32 v165, v165
	v_mul_f32_e32 v162, v66, v162
	v_mul_f32_e32 v163, v67, v163
	v_mul_f32_e32 v164, v68, v164
	v_mul_f32_e32 v165, v69, v165
	v_mul_f32_e32 v162, v74, v162
	v_mul_f32_e32 v163, v75, v163
	v_mul_f32_e32 v164, v76, v164
	v_mul_f32_e32 v165, v77, v165
	v_cvt_pk_bf16_f32 v172, v162, v163
	v_cvt_pk_bf16_f32 v173, v164, v165
	v_mul_f32_e32 v162, 0xbfb8aa3b, v70
	v_mul_f32_e32 v163, 0xbfb8aa3b, v71
	v_mul_f32_e32 v164, 0xbfb8aa3b, v72
	v_mul_f32_e32 v165, 0xbfb8aa3b, v73
	v_exp_f32_e32 v162, v162
	v_exp_f32_e32 v163, v163
	v_exp_f32_e32 v164, v164
	v_exp_f32_e32 v165, v165
	v_add_f32_e32 v162, 1.0, v162
	v_add_f32_e32 v163, 1.0, v163
	v_add_f32_e32 v164, 1.0, v164
	v_add_f32_e32 v165, 1.0, v165
	v_rcp_f32_e32 v162, v162
	v_rcp_f32_e32 v163, v163
	v_rcp_f32_e32 v164, v164
	v_rcp_f32_e32 v165, v165
	v_mul_f32_e32 v162, v70, v162
	v_mul_f32_e32 v163, v71, v163
	v_mul_f32_e32 v164, v72, v164
	v_mul_f32_e32 v165, v73, v165
	v_mul_f32_e32 v162, v78, v162
	v_mul_f32_e32 v163, v79, v163
	v_mul_f32_e32 v164, v80, v164
	v_mul_f32_e32 v165, v81, v165
	v_cvt_pk_bf16_f32 v174, v162, v163
	v_cvt_pk_bf16_f32 v175, v164, v165
	s_nop 1
	v_permlane16_swap_b32_e32 v172, v174
	v_permlane16_swap_b32_e32 v173, v175
	global_store_dwordx4 v176, v[172:175], s[4:5] offset:2048
